# G3: next unit's row scales loaded at K-loop start and published at epilogue start; epilogue no longer drains its tile stores
# baseline (speedup 1.0000x reference)
.LBB0_151:
	s_ashr_i32 s59, s58, 31
	s_lshl_b64 s[56:57], s[58:59], 19
	s_add_u32 s60, s0, s56
	s_addc_u32 s61, s1, s57
	s_and_b64 s[56:57], s[38:39], exec
	s_cselect_b32 s56, s61, s41
	s_cselect_b32 s57, s60, s40
	s_ashr_i32 s55, s54, 31
	s_lshl_b64 s[62:63], s[54:55], 19
	s_add_u32 s62, s3, s62
	s_addc_u32 s63, s28, s63
	s_and_b64 s[72:73], s[38:39], exec
	s_cselect_b32 s55, s63, s67
	s_cselect_b32 s80, s62, s66
	s_add_u32 s40, s40, 0x40080
	s_addc_u32 s41, s41, 0
	s_add_u32 s81, s66, 0x100
	v_mov_b32_e32 v10, 0
	s_addc_u32 s82, s67, 0
	s_mov_b32 s83, -2
	v_mov_b32_e32 v11, v10
	v_mov_b32_e32 v12, v10
	v_mov_b32_e32 v13, v10
	v_mov_b32_e32 v14, v10
	v_mov_b32_e32 v15, v10
	v_mov_b32_e32 v16, v10
	v_mov_b32_e32 v17, v10
	v_mov_b32_e32 v26, v10
	v_mov_b32_e32 v27, v10
	v_mov_b32_e32 v28, v10
	v_mov_b32_e32 v29, v10
	v_mov_b32_e32 v30, v10
	v_mov_b32_e32 v31, v10
	v_mov_b32_e32 v32, v10
	v_mov_b32_e32 v33, v10
	v_mov_b32_e32 v42, v10
	v_mov_b32_e32 v43, v10
	v_mov_b32_e32 v44, v10
	v_mov_b32_e32 v45, v10
	v_mov_b32_e32 v46, v10
	v_mov_b32_e32 v47, v10
	v_mov_b32_e32 v48, v10
	v_mov_b32_e32 v49, v10
	v_mov_b32_e32 v58, v10
	v_mov_b32_e32 v59, v10
	v_mov_b32_e32 v60, v10
	v_mov_b32_e32 v61, v10
	v_mov_b32_e32 v62, v10
	v_mov_b32_e32 v63, v10
	v_mov_b32_e32 v64, v10
	v_mov_b32_e32 v65, v10
	v_mov_b32_e32 v18, v10
	v_mov_b32_e32 v19, v10
	v_mov_b32_e32 v20, v10
	v_mov_b32_e32 v21, v10
	v_mov_b32_e32 v22, v10
	v_mov_b32_e32 v23, v10
	v_mov_b32_e32 v24, v10
	v_mov_b32_e32 v25, v10
	v_mov_b32_e32 v34, v10
	v_mov_b32_e32 v35, v10
	v_mov_b32_e32 v36, v10
	v_mov_b32_e32 v37, v10
	v_mov_b32_e32 v38, v10
	v_mov_b32_e32 v39, v10
	v_mov_b32_e32 v40, v10
	v_mov_b32_e32 v41, v10
	v_mov_b32_e32 v50, v10
	v_mov_b32_e32 v51, v10
	v_mov_b32_e32 v52, v10
	v_mov_b32_e32 v53, v10
	v_mov_b32_e32 v54, v10
	v_mov_b32_e32 v55, v10
	v_mov_b32_e32 v56, v10
	v_mov_b32_e32 v57, v10
	v_mov_b32_e32 v66, v10
	v_mov_b32_e32 v67, v10
	v_mov_b32_e32 v68, v10
	v_mov_b32_e32 v69, v10
	v_mov_b32_e32 v70, v10
	v_mov_b32_e32 v71, v10
	v_mov_b32_e32 v72, v10
	v_mov_b32_e32 v73, v10
	v_mov_b32_e32 v74, v10
	v_mov_b32_e32 v75, v10
	v_mov_b32_e32 v76, v10
	v_mov_b32_e32 v77, v10
	v_mov_b32_e32 v78, v10
	v_mov_b32_e32 v79, v10
	v_mov_b32_e32 v80, v10
	v_mov_b32_e32 v81, v10
	v_mov_b32_e32 v90, v10
	v_mov_b32_e32 v91, v10
	v_mov_b32_e32 v92, v10
	v_mov_b32_e32 v93, v10
	v_mov_b32_e32 v94, v10
	v_mov_b32_e32 v95, v10
	v_mov_b32_e32 v96, v10
	v_mov_b32_e32 v97, v10
	v_mov_b32_e32 v106, v10
	v_mov_b32_e32 v107, v10
	v_mov_b32_e32 v108, v10
	v_mov_b32_e32 v109, v10
	v_mov_b32_e32 v110, v10
	v_mov_b32_e32 v111, v10
	v_mov_b32_e32 v112, v10
	v_mov_b32_e32 v113, v10
	v_mov_b32_e32 v122, v10
	v_mov_b32_e32 v123, v10
	v_mov_b32_e32 v124, v10
	v_mov_b32_e32 v125, v10
	v_mov_b32_e32 v126, v10
	v_mov_b32_e32 v127, v10
	v_mov_b32_e32 v128, v10
	v_mov_b32_e32 v129, v10
	v_mov_b32_e32 v82, v10
	v_mov_b32_e32 v83, v10
	v_mov_b32_e32 v84, v10
	v_mov_b32_e32 v85, v10
	v_mov_b32_e32 v86, v10
	v_mov_b32_e32 v87, v10
	v_mov_b32_e32 v88, v10
	v_mov_b32_e32 v89, v10
	v_mov_b32_e32 v98, v10
	v_mov_b32_e32 v99, v10
	v_mov_b32_e32 v100, v10
	v_mov_b32_e32 v101, v10
	v_mov_b32_e32 v102, v10
	v_mov_b32_e32 v103, v10
	v_mov_b32_e32 v104, v10
	v_mov_b32_e32 v105, v10
	v_mov_b32_e32 v114, v10
	v_mov_b32_e32 v115, v10
	v_mov_b32_e32 v116, v10
	v_mov_b32_e32 v117, v10
	v_mov_b32_e32 v118, v10
	v_mov_b32_e32 v119, v10
	v_mov_b32_e32 v120, v10
	v_mov_b32_e32 v121, v10
	v_mov_b32_e32 v130, v10
	v_mov_b32_e32 v131, v10
	v_mov_b32_e32 v132, v10
	v_mov_b32_e32 v133, v10
	v_mov_b32_e32 v134, v10
	v_mov_b32_e32 v135, v10
	v_mov_b32_e32 v136, v10
	v_mov_b32_e32 v137, v10
	s_and_b64 vcc, exec, s[38:39]
	s_cbranch_vccz .Lg3_rs_skip
	s_lshl_b64 s[100:101], s[58:59], 14
	v_lshl_add_u64 v[6:7], v[146:147], 0, s[100:101]
	global_load_dwordx4 v[2:5], v[6:7], off offset:16
	s_nop 0
	global_load_dwordx4 v[6:9], v[6:7], off
.Lg3_rs_skip:
.LBB0_152:
	s_add_u32 s66, s40, 0xfffc0080
	s_addc_u32 s67, s41, -1
	s_add_i32 s84, 0, 0x10000
	s_cmp_eq_u32 s83, 12
	s_cselect_b32 s73, s56, s67
	s_cselect_b32 s72, s57, s66
	v_add_u32_e32 v154, s84, v157
	s_cselect_b32 s67, s55, s82
	s_cselect_b32 s66, s80, s81
	s_add_i32 s87, 0, 0x14000
	ds_read_b128 v[162:165], v154
	ds_read_b128 v[166:169], v154 offset:1024
	ds_read_b128 v[170:173], v154 offset:2048
	ds_read_b128 v[174:177], v154 offset:3072
	v_add_u32_e32 v154, s87, v157
	ds_read_b128 v[178:181], v154
	ds_read_b128 v[182:185], v154 offset:1024
	ds_read_b128 v[186:189], v154 offset:2048
	ds_read_b128 v[190:193], v154 offset:3072
	v_lshl_add_u64 v[154:155], s[40:41], 0, v[148:149]
	s_add_i32 m0, s42, 0xc000
	ds_read_b128 v[196:199], v160
	ds_read_b128 v[200:203], v160 offset:1024
	ds_read_b128 v[204:207], v160 offset:2048
	ds_read_b128 v[208:211], v160 offset:3072
	ds_read_b128 v[212:215], v160 offset:4096
	ds_read_b128 v[216:219], v160 offset:5120
	ds_read_b128 v[228:231], v160 offset:6144
	ds_read_b128 v[232:235], v160 offset:7168
	global_load_lds_dwordx4 v[154:155], off
	v_lshl_add_u64 v[154:155], s[40:41], 0, v[150:151]
	s_add_i32 m0, s42, 0xe000
	s_nop 0
	global_load_lds_dwordx4 v[154:155], off
	s_waitcnt vmcnt(8)
	s_waitcnt lgkmcnt(0)
	s_barrier
	s_setprio 1
	s_waitcnt lgkmcnt(0)
	v_mfma_f32_16x16x32_f16 v[134:137], v[162:165], v[196:199], v[134:137]
	v_mfma_f32_16x16x32_f16 v[130:133], v[170:173], v[196:199], v[130:133]
	v_mfma_f32_16x16x32_f16 v[118:121], v[162:165], v[204:207], v[118:121]
	v_mfma_f32_16x16x32_f16 v[114:117], v[170:173], v[204:207], v[114:117]
	v_mfma_f32_16x16x32_f16 v[102:105], v[162:165], v[212:215], v[102:105]
	v_mfma_f32_16x16x32_f16 v[98:101], v[170:173], v[212:215], v[98:101]
	v_mfma_f32_16x16x32_f16 v[86:89], v[162:165], v[228:231], v[86:89]
	v_mfma_f32_16x16x32_f16 v[82:85], v[170:173], v[228:231], v[82:85]
	v_mfma_f32_16x16x32_f16 v[134:137], v[166:169], v[200:203], v[134:137]
	v_mfma_f32_16x16x32_f16 v[130:133], v[174:177], v[200:203], v[130:133]
	v_mfma_f32_16x16x32_f16 v[118:121], v[166:169], v[208:211], v[118:121]
	v_mfma_f32_16x16x32_f16 v[114:117], v[174:177], v[208:211], v[114:117]
	v_mfma_f32_16x16x32_f16 v[102:105], v[166:169], v[216:219], v[102:105]
	v_mfma_f32_16x16x32_f16 v[98:101], v[174:177], v[216:219], v[98:101]
	v_mfma_f32_16x16x32_f16 v[86:89], v[166:169], v[232:235], v[86:89]
	v_mfma_f32_16x16x32_f16 v[82:85], v[174:177], v[232:235], v[82:85]
	s_setprio 0
	s_setprio 1
	v_mfma_f32_16x16x32_f16 v[126:129], v[178:181], v[196:199], v[126:129]
	v_mfma_f32_16x16x32_f16 v[122:125], v[186:189], v[196:199], v[122:125]
	v_mfma_f32_16x16x32_f16 v[110:113], v[178:181], v[204:207], v[110:113]
	v_mfma_f32_16x16x32_f16 v[106:109], v[186:189], v[204:207], v[106:109]
	v_mfma_f32_16x16x32_f16 v[94:97], v[178:181], v[212:215], v[94:97]
	v_mfma_f32_16x16x32_f16 v[90:93], v[186:189], v[212:215], v[90:93]
	v_mfma_f32_16x16x32_f16 v[78:81], v[178:181], v[228:231], v[78:81]
	v_mfma_f32_16x16x32_f16 v[74:77], v[186:189], v[228:231], v[74:77]
	v_mfma_f32_16x16x32_f16 v[126:129], v[182:185], v[200:203], v[126:129]
	v_mfma_f32_16x16x32_f16 v[122:125], v[190:193], v[200:203], v[122:125]
	v_mfma_f32_16x16x32_f16 v[110:113], v[182:185], v[208:211], v[110:113]
	v_mfma_f32_16x16x32_f16 v[106:109], v[190:193], v[208:211], v[106:109]
	v_mfma_f32_16x16x32_f16 v[94:97], v[182:185], v[216:219], v[94:97]
	v_mfma_f32_16x16x32_f16 v[90:93], v[190:193], v[216:219], v[90:93]
	v_mfma_f32_16x16x32_f16 v[78:81], v[182:185], v[232:235], v[78:81]
	v_mfma_f32_16x16x32_f16 v[74:77], v[190:193], v[232:235], v[74:77]
	s_setprio 0
	s_barrier
	s_add_i32 s84, s84, s29
	v_lshl_add_u64 v[154:155], s[66:67], 0, v[142:143]
	s_mov_b32 m0, s84
	ds_read_b128 v[196:199], v160 offset:16384
	ds_read_b128 v[200:203], v160 offset:17408
	ds_read_b128 v[204:207], v160 offset:18432
	ds_read_b128 v[208:211], v160 offset:19456
	ds_read_b128 v[212:215], v160 offset:20480
	ds_read_b128 v[216:219], v160 offset:21504
	ds_read_b128 v[228:231], v160 offset:22528
	ds_read_b128 v[232:235], v160 offset:23552
	global_load_lds_dwordx4 v[154:155], off
	s_add_i32 m0, s84, 0x2000
	s_add_u32 s84, s66, 0x40000
	v_lshl_add_u64 v[236:237], s[66:67], 0, v[138:139]
	s_addc_u32 s85, s67, 0
	s_add_i32 s87, s87, s29
	global_load_lds_dwordx4 v[236:237], off
	v_lshl_add_u64 v[238:239], s[84:85], 0, v[142:143]
	s_mov_b32 m0, s87
	v_lshl_add_u64 v[240:241], s[72:73], 0, v[140:141]
	global_load_lds_dwordx4 v[238:239], off
	v_lshl_add_u64 v[238:239], s[84:85], 0, v[138:139]
	s_add_i32 m0, s87, 0x2000
	s_nop 0
	global_load_lds_dwordx4 v[238:239], off
	v_lshl_add_u64 v[238:239], s[72:73], 0, v[144:145]
	s_mov_b32 m0, s42
	s_nop 0
	global_load_lds_dwordx4 v[238:239], off
	s_mov_b32 m0, s43
	s_nop 0
	global_load_lds_dwordx4 v[240:241], off
	s_waitcnt vmcnt(8)
	s_waitcnt lgkmcnt(0)
	s_barrier
	s_setprio 1
	s_waitcnt lgkmcnt(0)
	v_mfma_f32_16x16x32_f16 v[70:73], v[162:165], v[196:199], v[70:73]
	v_mfma_f32_16x16x32_f16 v[66:69], v[170:173], v[196:199], v[66:69]
	v_mfma_f32_16x16x32_f16 v[54:57], v[162:165], v[204:207], v[54:57]
	v_mfma_f32_16x16x32_f16 v[50:53], v[170:173], v[204:207], v[50:53]
	v_mfma_f32_16x16x32_f16 v[38:41], v[162:165], v[212:215], v[38:41]
	v_mfma_f32_16x16x32_f16 v[34:37], v[170:173], v[212:215], v[34:37]
	v_mfma_f32_16x16x32_f16 v[22:25], v[162:165], v[228:231], v[22:25]
	v_mfma_f32_16x16x32_f16 v[18:21], v[170:173], v[228:231], v[18:21]
	v_mfma_f32_16x16x32_f16 v[70:73], v[166:169], v[200:203], v[70:73]
	v_mfma_f32_16x16x32_f16 v[66:69], v[174:177], v[200:203], v[66:69]
	v_mfma_f32_16x16x32_f16 v[54:57], v[166:169], v[208:211], v[54:57]
	v_mfma_f32_16x16x32_f16 v[50:53], v[174:177], v[208:211], v[50:53]
	v_mfma_f32_16x16x32_f16 v[38:41], v[166:169], v[216:219], v[38:41]
	v_mfma_f32_16x16x32_f16 v[34:37], v[174:177], v[216:219], v[34:37]
	v_mfma_f32_16x16x32_f16 v[22:25], v[166:169], v[232:235], v[22:25]
	v_mfma_f32_16x16x32_f16 v[18:21], v[174:177], v[232:235], v[18:21]
	s_setprio 0
	s_setprio 1
	v_mfma_f32_16x16x32_f16 v[62:65], v[178:181], v[196:199], v[62:65]
	v_mfma_f32_16x16x32_f16 v[58:61], v[186:189], v[196:199], v[58:61]
	v_mfma_f32_16x16x32_f16 v[46:49], v[178:181], v[204:207], v[46:49]
	v_mfma_f32_16x16x32_f16 v[42:45], v[186:189], v[204:207], v[42:45]
	v_mfma_f32_16x16x32_f16 v[30:33], v[178:181], v[212:215], v[30:33]
	v_mfma_f32_16x16x32_f16 v[26:29], v[186:189], v[212:215], v[26:29]
	v_mfma_f32_16x16x32_f16 v[14:17], v[178:181], v[228:231], v[14:17]
	v_mfma_f32_16x16x32_f16 v[10:13], v[186:189], v[228:231], v[10:13]
	v_mfma_f32_16x16x32_f16 v[62:65], v[182:185], v[200:203], v[62:65]
	v_mfma_f32_16x16x32_f16 v[58:61], v[190:193], v[200:203], v[58:61]
	v_mfma_f32_16x16x32_f16 v[46:49], v[182:185], v[208:211], v[46:49]
	v_mfma_f32_16x16x32_f16 v[42:45], v[190:193], v[208:211], v[42:45]
	v_mfma_f32_16x16x32_f16 v[30:33], v[182:185], v[216:219], v[30:33]
	v_mfma_f32_16x16x32_f16 v[26:29], v[190:193], v[216:219], v[26:29]
	v_mfma_f32_16x16x32_f16 v[14:17], v[182:185], v[232:235], v[14:17]
	v_mfma_f32_16x16x32_f16 v[10:13], v[190:193], v[232:235], v[10:13]
	s_setprio 0
	s_barrier
	s_add_i32 s84, 0, 0x18000
	v_add_u32_e32 v161, s84, v157
	s_add_i32 s85, 0, 0x1c000
	ds_read_b128 v[162:165], v161
	ds_read_b128 v[166:169], v161 offset:1024
	ds_read_b128 v[170:173], v161 offset:2048
	ds_read_b128 v[174:177], v161 offset:3072
	v_add_u32_e32 v161, s85, v157
	ds_read_b128 v[178:181], v161
	ds_read_b128 v[182:185], v161 offset:1024
	ds_read_b128 v[186:189], v161 offset:2048
	ds_read_b128 v[190:193], v161 offset:3072
	s_add_u32 s72, s72, 0x40000
	s_addc_u32 s73, s73, 0
	s_mov_b32 m0, s46
	v_lshl_add_u64 v[242:243], s[72:73], 0, v[144:145]
	ds_read_b128 v[196:199], v160 offset:32768
	ds_read_b128 v[200:203], v160 offset:33792
	ds_read_b128 v[204:207], v160 offset:34816
	ds_read_b128 v[208:211], v160 offset:35840
	ds_read_b128 v[212:215], v160 offset:36864
	ds_read_b128 v[216:219], v160 offset:37888
	ds_read_b128 v[228:231], v160 offset:38912
	ds_read_b128 v[232:235], v160 offset:39936
	global_load_lds_dwordx4 v[242:243], off
	v_lshl_add_u64 v[242:243], s[72:73], 0, v[140:141]
	s_mov_b32 m0, s47
	s_nop 0
	global_load_lds_dwordx4 v[242:243], off
	s_waitcnt vmcnt(8)
	s_waitcnt lgkmcnt(0)
	s_barrier
	s_setprio 1
	s_waitcnt lgkmcnt(0)
	v_mfma_f32_16x16x32_f16 v[134:137], v[162:165], v[196:199], v[134:137]
	v_mfma_f32_16x16x32_f16 v[130:133], v[170:173], v[196:199], v[130:133]
	v_mfma_f32_16x16x32_f16 v[118:121], v[162:165], v[204:207], v[118:121]
	v_mfma_f32_16x16x32_f16 v[114:117], v[170:173], v[204:207], v[114:117]
	v_mfma_f32_16x16x32_f16 v[102:105], v[162:165], v[212:215], v[102:105]
	v_mfma_f32_16x16x32_f16 v[98:101], v[170:173], v[212:215], v[98:101]
	v_mfma_f32_16x16x32_f16 v[86:89], v[162:165], v[228:231], v[86:89]
	v_mfma_f32_16x16x32_f16 v[82:85], v[170:173], v[228:231], v[82:85]
	v_mfma_f32_16x16x32_f16 v[134:137], v[166:169], v[200:203], v[134:137]
	v_mfma_f32_16x16x32_f16 v[130:133], v[174:177], v[200:203], v[130:133]
	v_mfma_f32_16x16x32_f16 v[118:121], v[166:169], v[208:211], v[118:121]
	v_mfma_f32_16x16x32_f16 v[114:117], v[174:177], v[208:211], v[114:117]
	v_mfma_f32_16x16x32_f16 v[102:105], v[166:169], v[216:219], v[102:105]
	v_mfma_f32_16x16x32_f16 v[98:101], v[174:177], v[216:219], v[98:101]
	v_mfma_f32_16x16x32_f16 v[86:89], v[166:169], v[232:235], v[86:89]
	v_mfma_f32_16x16x32_f16 v[82:85], v[174:177], v[232:235], v[82:85]
	s_setprio 0
	s_setprio 1
	v_mfma_f32_16x16x32_f16 v[126:129], v[178:181], v[196:199], v[126:129]
	v_mfma_f32_16x16x32_f16 v[122:125], v[186:189], v[196:199], v[122:125]
	v_mfma_f32_16x16x32_f16 v[110:113], v[178:181], v[204:207], v[110:113]
	v_mfma_f32_16x16x32_f16 v[106:109], v[186:189], v[204:207], v[106:109]
	v_mfma_f32_16x16x32_f16 v[94:97], v[178:181], v[212:215], v[94:97]
	v_mfma_f32_16x16x32_f16 v[90:93], v[186:189], v[212:215], v[90:93]
	v_mfma_f32_16x16x32_f16 v[78:81], v[178:181], v[228:231], v[78:81]
	v_mfma_f32_16x16x32_f16 v[74:77], v[186:189], v[228:231], v[74:77]
	v_mfma_f32_16x16x32_f16 v[126:129], v[182:185], v[200:203], v[126:129]
	v_mfma_f32_16x16x32_f16 v[122:125], v[190:193], v[200:203], v[122:125]
	v_mfma_f32_16x16x32_f16 v[110:113], v[182:185], v[208:211], v[110:113]
	v_mfma_f32_16x16x32_f16 v[106:109], v[190:193], v[208:211], v[106:109]
	v_mfma_f32_16x16x32_f16 v[94:97], v[182:185], v[216:219], v[94:97]
	v_mfma_f32_16x16x32_f16 v[90:93], v[190:193], v[216:219], v[90:93]
	v_mfma_f32_16x16x32_f16 v[78:81], v[182:185], v[232:235], v[78:81]
	v_mfma_f32_16x16x32_f16 v[74:77], v[190:193], v[232:235], v[74:77]
	s_setprio 0
	s_barrier
	s_add_i32 s72, s84, s29
	v_lshl_add_u64 v[154:155], v[154:155], 0, s[34:35]
	s_mov_b32 m0, s72
	ds_read_b128 v[196:199], v160 offset:49152
	ds_read_b128 v[200:203], v160 offset:50176
	ds_read_b128 v[204:207], v160 offset:51200
	ds_read_b128 v[208:211], v160 offset:52224
	ds_read_b128 v[212:215], v160 offset:53248
	ds_read_b128 v[216:219], v160 offset:54272
	ds_read_b128 v[228:231], v160 offset:55296
	ds_read_b128 v[232:235], v160 offset:56320
	global_load_lds_dwordx4 v[154:155], off
	s_add_i32 m0, s72, 0x2000
	s_add_u32 s66, s66, 0x40080
	v_lshl_add_u64 v[154:155], v[236:237], 0, s[34:35]
	s_addc_u32 s67, s67, 0
	s_add_i32 s72, s85, s29
	global_load_lds_dwordx4 v[154:155], off
	v_lshl_add_u64 v[154:155], s[66:67], 0, v[142:143]
	s_mov_b32 m0, s72
	s_nop 0
	global_load_lds_dwordx4 v[154:155], off
	v_lshl_add_u64 v[154:155], s[66:67], 0, v[138:139]
	s_add_i32 m0, s72, 0x2000
	s_nop 0
	global_load_lds_dwordx4 v[154:155], off
	v_lshl_add_u64 v[154:155], v[238:239], 0, s[34:35]
	s_mov_b32 m0, s68
	s_nop 0
	global_load_lds_dwordx4 v[154:155], off
	v_lshl_add_u64 v[154:155], v[240:241], 0, s[34:35]
	s_mov_b32 m0, s69
	s_nop 0
	global_load_lds_dwordx4 v[154:155], off
	s_waitcnt vmcnt(8)
	s_waitcnt lgkmcnt(0)
	s_barrier
	s_setprio 1
	s_waitcnt lgkmcnt(0)
	v_mfma_f32_16x16x32_f16 v[70:73], v[162:165], v[196:199], v[70:73]
	v_mfma_f32_16x16x32_f16 v[66:69], v[170:173], v[196:199], v[66:69]
	v_mfma_f32_16x16x32_f16 v[54:57], v[162:165], v[204:207], v[54:57]
	v_mfma_f32_16x16x32_f16 v[50:53], v[170:173], v[204:207], v[50:53]
	v_mfma_f32_16x16x32_f16 v[38:41], v[162:165], v[212:215], v[38:41]
	v_mfma_f32_16x16x32_f16 v[34:37], v[170:173], v[212:215], v[34:37]
	v_mfma_f32_16x16x32_f16 v[22:25], v[162:165], v[228:231], v[22:25]
	v_mfma_f32_16x16x32_f16 v[18:21], v[170:173], v[228:231], v[18:21]
	v_mfma_f32_16x16x32_f16 v[70:73], v[166:169], v[200:203], v[70:73]
	v_mfma_f32_16x16x32_f16 v[66:69], v[174:177], v[200:203], v[66:69]
	v_mfma_f32_16x16x32_f16 v[54:57], v[166:169], v[208:211], v[54:57]
	v_mfma_f32_16x16x32_f16 v[50:53], v[174:177], v[208:211], v[50:53]
	v_mfma_f32_16x16x32_f16 v[38:41], v[166:169], v[216:219], v[38:41]
	v_mfma_f32_16x16x32_f16 v[34:37], v[174:177], v[216:219], v[34:37]
	v_mfma_f32_16x16x32_f16 v[22:25], v[166:169], v[232:235], v[22:25]
	v_mfma_f32_16x16x32_f16 v[18:21], v[174:177], v[232:235], v[18:21]
	s_setprio 0
	s_setprio 1
	v_mfma_f32_16x16x32_f16 v[62:65], v[178:181], v[196:199], v[62:65]
	v_mfma_f32_16x16x32_f16 v[58:61], v[186:189], v[196:199], v[58:61]
	v_mfma_f32_16x16x32_f16 v[46:49], v[178:181], v[204:207], v[46:49]
	v_mfma_f32_16x16x32_f16 v[42:45], v[186:189], v[204:207], v[42:45]
	v_mfma_f32_16x16x32_f16 v[30:33], v[178:181], v[212:215], v[30:33]
	v_mfma_f32_16x16x32_f16 v[26:29], v[186:189], v[212:215], v[26:29]
	v_mfma_f32_16x16x32_f16 v[14:17], v[178:181], v[228:231], v[14:17]
	v_mfma_f32_16x16x32_f16 v[10:13], v[186:189], v[228:231], v[10:13]
	v_mfma_f32_16x16x32_f16 v[62:65], v[182:185], v[200:203], v[62:65]
	v_mfma_f32_16x16x32_f16 v[58:61], v[190:193], v[200:203], v[58:61]
	v_mfma_f32_16x16x32_f16 v[46:49], v[182:185], v[208:211], v[46:49]
	v_mfma_f32_16x16x32_f16 v[42:45], v[190:193], v[208:211], v[42:45]
	v_mfma_f32_16x16x32_f16 v[30:33], v[182:185], v[216:219], v[30:33]
	v_mfma_f32_16x16x32_f16 v[26:29], v[190:193], v[216:219], v[26:29]
	v_mfma_f32_16x16x32_f16 v[14:17], v[182:185], v[232:235], v[14:17]
	v_mfma_f32_16x16x32_f16 v[10:13], v[190:193], v[232:235], v[10:13]
	s_setprio 0
	s_barrier
	s_add_i32 s83, s83, 2
	s_add_u32 s40, s40, 0x100
	s_addc_u32 s41, s41, 0
	s_add_u32 s81, s81, 0x100
	s_addc_u32 s82, s82, 0
	s_cmp_gt_u32 s83, 13
	s_cbranch_scc0 .LBB0_152
	s_and_b64 vcc, exec, s[48:49]
	s_cbranch_vccz .LBB0_155
	s_barrier
.LBB0_155:
	v_cndmask_b32_e64 v154, 0, 1, s[38:39]
	v_cmp_ne_u32_e64 s[40:41], 1, v154
	s_andn2_b64 vcc, exec, s[38:39]
	v_readlane_b32 s87, v254, 61
	v_readlane_b32 s80, v254, 62
	s_cbranch_vccnz .LBB0_157
	s_waitcnt vmcnt(0)
	v_add_f32_e32 v244, v6, v7
	v_add_f32_e32 v245, v8, v9
	v_add_f32_e32 v244, v244, v245
	v_add_f32_e32 v245, v2, v3
	v_add_f32_e32 v246, v4, v5
	v_add_f32_e32 v245, v245, v246
	v_add_f32_e32 v244, v245, v244
	ds_bpermute_b32 v245, v1, v244
	s_and_saveexec_b64 s[38:39], s[36:37]
	s_cbranch_execz .Lg3_rsput_done
	s_waitcnt lgkmcnt(0)
	v_add_f32_e32 v244, v244, v245
	v_fmamk_f32 v244, v244, 0x3a800000, v220
	v_rsq_f32_e32 v244, v244
	s_lshl_b32 s100, s76, 10
	s_and_b32 s100, s100, 0x400
	v_add_u32_e32 v245, s100, v159
	ds_write_b32 v245, v244
.Lg3_rsput_done:
	s_or_b64 exec, exec, s[38:39]
.LBB0_157:
	s_lshl_b32 s38, s79, 10
	s_and_b32 s38, s38, 0x400
	v_add_u32_e32 v161, s38, v158
	ds_read_b32 v162, v161
	v_lshl_add_u32 v154, s78, 8, v156
	s_lshl_b32 s38, s77, 8
	v_ashrrev_i32_e32 v155, 31, v154
	s_ashr_i32 s39, s38, 31
	v_lshlrev_b64 v[164:165], 13, v[154:155]
	v_lshl_add_u64 v[164:165], s[30:31], 0, v[164:165]
	s_lshl_b64 s[38:39], s[38:39], 1
	v_lshl_add_u64 v[164:165], v[164:165], 0, s[38:39]
	s_waitcnt lgkmcnt(0)
	v_pk_mul_f32 v[136:137], v[136:137], v[162:163] op_sel_hi:[1,0]
	v_pk_mul_f32 v[134:135], v[134:135], v[162:163] op_sel_hi:[1,0]
	v_pk_mul_f32 v[132:133], v[132:133], v[162:163] op_sel_hi:[1,0]
	v_pk_mul_f32 v[130:131], v[130:131], v[162:163] op_sel_hi:[1,0]
	v_lshl_add_u64 v[164:165], v[164:165], 0, s[50:51]
	v_max_f32_e32 v137, 0, v137
	v_max_f32_e32 v136, 0, v136
	v_max_f32_e32 v135, 0, v135
	v_max_f32_e32 v134, 0, v134
	v_max_f32_e32 v133, 0, v133
	v_max_f32_e32 v132, 0, v132
	v_max_f32_e32 v131, 0, v131
	v_max_f32_e32 v130, 0, v130
	v_pk_mul_f32 v[124:125], v[124:125], v[162:163] op_sel_hi:[1,0]
	v_pk_mul_f32 v[122:123], v[122:123], v[162:163] op_sel_hi:[1,0]
	v_lshl_add_u64 v[164:165], v[164:165], 0, v[152:153]
	v_pk_mul_f32 v[136:137], v[136:137], v[136:137]
	v_pk_mul_f32 v[134:135], v[134:135], v[134:135]
	v_pk_mul_f32 v[166:167], v[132:133], v[132:133]
	v_pk_mul_f32 v[132:133], v[130:131], v[130:131]
	v_cvt_pk_bf16_f32 v130, v134, v135
	v_cvt_pk_bf16_f32 v131, v136, v137
	v_pk_mul_f32 v[128:129], v[128:129], v[162:163] op_sel_hi:[1,0]
	v_pk_mul_f32 v[126:127], v[126:127], v[162:163] op_sel_hi:[1,0]
	v_max_f32_e32 v125, 0, v125
	v_max_f32_e32 v124, 0, v124
	v_max_f32_e32 v123, 0, v123
	v_max_f32_e32 v122, 0, v122
	v_cvt_pk_bf16_f32 v132, v132, v133
	v_cvt_pk_bf16_f32 v133, v166, v167
	global_store_dwordx4 v[164:165], v[130:133], off
	v_max_f32_e32 v129, 0, v129
	v_max_f32_e32 v128, 0, v128
	v_max_f32_e32 v127, 0, v127
	v_max_f32_e32 v126, 0, v126
	v_pk_mul_f32 v[130:131], v[124:125], v[124:125]
	v_pk_mul_f32 v[124:125], v[122:123], v[122:123]
	v_pk_mul_f32 v[128:129], v[128:129], v[128:129]
	v_pk_mul_f32 v[126:127], v[126:127], v[126:127]
	s_and_b64 vcc, exec, s[40:41]
	v_cvt_pk_bf16_f32 v122, v126, v127
	v_cvt_pk_bf16_f32 v123, v128, v129
	v_cvt_pk_bf16_f32 v124, v124, v125
	v_cvt_pk_bf16_f32 v125, v130, v131
	global_store_dwordx4 v[164:165], v[122:125], off offset:256
	ds_read_b32 v124, v161 offset:64
	s_waitcnt lgkmcnt(0)
	v_pk_mul_f32 v[120:121], v[120:121], v[124:125] op_sel_hi:[1,0]
	v_or_b32_e32 v122, 16, v154
	v_ashrrev_i32_e32 v123, 31, v122
	v_lshlrev_b64 v[122:123], 13, v[122:123]
	v_lshl_add_u64 v[122:123], s[30:31], 0, v[122:123]
	v_lshl_add_u64 v[122:123], v[122:123], 0, s[38:39]
	v_pk_mul_f32 v[118:119], v[118:119], v[124:125] op_sel_hi:[1,0]
	v_pk_mul_f32 v[116:117], v[116:117], v[124:125] op_sel_hi:[1,0]
	v_pk_mul_f32 v[114:115], v[114:115], v[124:125] op_sel_hi:[1,0]
	v_lshl_add_u64 v[122:123], v[122:123], 0, s[50:51]
	v_max_f32_e32 v121, 0, v121
	v_max_f32_e32 v120, 0, v120
	v_max_f32_e32 v119, 0, v119
	v_max_f32_e32 v118, 0, v118
	v_max_f32_e32 v117, 0, v117
	v_max_f32_e32 v116, 0, v116
	v_max_f32_e32 v115, 0, v115
	v_max_f32_e32 v114, 0, v114
	v_pk_mul_f32 v[108:109], v[108:109], v[124:125] op_sel_hi:[1,0]
	v_pk_mul_f32 v[106:107], v[106:107], v[124:125] op_sel_hi:[1,0]
	v_lshl_add_u64 v[122:123], v[122:123], 0, v[152:153]
	v_pk_mul_f32 v[120:121], v[120:121], v[120:121]
	v_pk_mul_f32 v[118:119], v[118:119], v[118:119]
	v_pk_mul_f32 v[126:127], v[116:117], v[116:117]
	v_pk_mul_f32 v[116:117], v[114:115], v[114:115]
	v_cvt_pk_bf16_f32 v114, v118, v119
	v_cvt_pk_bf16_f32 v115, v120, v121
	v_pk_mul_f32 v[112:113], v[112:113], v[124:125] op_sel_hi:[1,0]
	v_pk_mul_f32 v[110:111], v[110:111], v[124:125] op_sel_hi:[1,0]
	v_max_f32_e32 v109, 0, v109
	v_max_f32_e32 v108, 0, v108
	v_max_f32_e32 v107, 0, v107
	v_max_f32_e32 v106, 0, v106
	v_cvt_pk_bf16_f32 v116, v116, v117
	v_cvt_pk_bf16_f32 v117, v126, v127
	global_store_dwordx4 v[122:123], v[114:117], off
	v_max_f32_e32 v113, 0, v113
	v_max_f32_e32 v112, 0, v112
	v_max_f32_e32 v111, 0, v111
	v_max_f32_e32 v110, 0, v110
	v_pk_mul_f32 v[114:115], v[108:109], v[108:109]
	v_pk_mul_f32 v[108:109], v[106:107], v[106:107]
	v_pk_mul_f32 v[112:113], v[112:113], v[112:113]
	v_pk_mul_f32 v[110:111], v[110:111], v[110:111]
	s_nop 0
	v_cvt_pk_bf16_f32 v106, v110, v111
	v_cvt_pk_bf16_f32 v107, v112, v113
	v_cvt_pk_bf16_f32 v108, v108, v109
	v_cvt_pk_bf16_f32 v109, v114, v115
	global_store_dwordx4 v[122:123], v[106:109], off offset:256
	ds_read_b32 v108, v161 offset:128
	s_waitcnt lgkmcnt(0)
	v_pk_mul_f32 v[104:105], v[104:105], v[108:109] op_sel_hi:[1,0]
	v_or_b32_e32 v106, 32, v154
	v_ashrrev_i32_e32 v107, 31, v106
	v_lshlrev_b64 v[106:107], 13, v[106:107]
	v_lshl_add_u64 v[106:107], s[30:31], 0, v[106:107]
	v_lshl_add_u64 v[106:107], v[106:107], 0, s[38:39]
	v_pk_mul_f32 v[102:103], v[102:103], v[108:109] op_sel_hi:[1,0]
	v_pk_mul_f32 v[100:101], v[100:101], v[108:109] op_sel_hi:[1,0]
	v_pk_mul_f32 v[98:99], v[98:99], v[108:109] op_sel_hi:[1,0]
	v_lshl_add_u64 v[106:107], v[106:107], 0, s[50:51]
	v_max_f32_e32 v105, 0, v105
	v_max_f32_e32 v104, 0, v104
	v_max_f32_e32 v103, 0, v103
	v_max_f32_e32 v102, 0, v102
	v_max_f32_e32 v101, 0, v101
	v_max_f32_e32 v100, 0, v100
	v_max_f32_e32 v99, 0, v99
	v_max_f32_e32 v98, 0, v98
	v_pk_mul_f32 v[92:93], v[92:93], v[108:109] op_sel_hi:[1,0]
	v_pk_mul_f32 v[90:91], v[90:91], v[108:109] op_sel_hi:[1,0]
	v_lshl_add_u64 v[106:107], v[106:107], 0, v[152:153]
	v_pk_mul_f32 v[104:105], v[104:105], v[104:105]
	v_pk_mul_f32 v[102:103], v[102:103], v[102:103]
	v_pk_mul_f32 v[110:111], v[100:101], v[100:101]
	v_pk_mul_f32 v[100:101], v[98:99], v[98:99]
	v_cvt_pk_bf16_f32 v98, v102, v103
	v_cvt_pk_bf16_f32 v99, v104, v105
	v_pk_mul_f32 v[96:97], v[96:97], v[108:109] op_sel_hi:[1,0]
	v_pk_mul_f32 v[94:95], v[94:95], v[108:109] op_sel_hi:[1,0]
	v_max_f32_e32 v93, 0, v93
	v_max_f32_e32 v92, 0, v92
	v_max_f32_e32 v91, 0, v91
	v_max_f32_e32 v90, 0, v90
	v_cvt_pk_bf16_f32 v100, v100, v101
	v_cvt_pk_bf16_f32 v101, v110, v111
	global_store_dwordx4 v[106:107], v[98:101], off
	v_max_f32_e32 v97, 0, v97
	v_max_f32_e32 v96, 0, v96
	v_max_f32_e32 v95, 0, v95
	v_max_f32_e32 v94, 0, v94
	v_pk_mul_f32 v[98:99], v[92:93], v[92:93]
	v_pk_mul_f32 v[92:93], v[90:91], v[90:91]
	v_pk_mul_f32 v[96:97], v[96:97], v[96:97]
	v_pk_mul_f32 v[94:95], v[94:95], v[94:95]
	s_nop 0
	v_cvt_pk_bf16_f32 v90, v94, v95
	v_cvt_pk_bf16_f32 v91, v96, v97
	v_cvt_pk_bf16_f32 v92, v92, v93
	v_cvt_pk_bf16_f32 v93, v98, v99
	global_store_dwordx4 v[106:107], v[90:93], off offset:256
	ds_read_b32 v92, v161 offset:192
	s_waitcnt lgkmcnt(0)
	v_pk_mul_f32 v[88:89], v[88:89], v[92:93] op_sel_hi:[1,0]
	v_or_b32_e32 v90, 48, v154
	v_ashrrev_i32_e32 v91, 31, v90
	v_lshlrev_b64 v[90:91], 13, v[90:91]
	v_lshl_add_u64 v[90:91], s[30:31], 0, v[90:91]
	v_lshl_add_u64 v[90:91], v[90:91], 0, s[38:39]
	v_pk_mul_f32 v[86:87], v[86:87], v[92:93] op_sel_hi:[1,0]
	v_pk_mul_f32 v[84:85], v[84:85], v[92:93] op_sel_hi:[1,0]
	v_pk_mul_f32 v[82:83], v[82:83], v[92:93] op_sel_hi:[1,0]
	v_lshl_add_u64 v[90:91], v[90:91], 0, s[50:51]
	v_max_f32_e32 v89, 0, v89
	v_max_f32_e32 v88, 0, v88
	v_max_f32_e32 v87, 0, v87
	v_max_f32_e32 v86, 0, v86
	v_max_f32_e32 v85, 0, v85
	v_max_f32_e32 v84, 0, v84
	v_max_f32_e32 v83, 0, v83
	v_max_f32_e32 v82, 0, v82
	v_pk_mul_f32 v[76:77], v[76:77], v[92:93] op_sel_hi:[1,0]
	v_pk_mul_f32 v[74:75], v[74:75], v[92:93] op_sel_hi:[1,0]
	v_lshl_add_u64 v[90:91], v[90:91], 0, v[152:153]
	v_pk_mul_f32 v[88:89], v[88:89], v[88:89]
	v_pk_mul_f32 v[86:87], v[86:87], v[86:87]
	v_pk_mul_f32 v[94:95], v[84:85], v[84:85]
	v_pk_mul_f32 v[84:85], v[82:83], v[82:83]
	v_cvt_pk_bf16_f32 v82, v86, v87
	v_cvt_pk_bf16_f32 v83, v88, v89
	v_pk_mul_f32 v[80:81], v[80:81], v[92:93] op_sel_hi:[1,0]
	v_pk_mul_f32 v[78:79], v[78:79], v[92:93] op_sel_hi:[1,0]
	v_max_f32_e32 v77, 0, v77
	v_max_f32_e32 v76, 0, v76
	v_max_f32_e32 v75, 0, v75
	v_max_f32_e32 v74, 0, v74
	v_cvt_pk_bf16_f32 v84, v84, v85
	v_cvt_pk_bf16_f32 v85, v94, v95
	global_store_dwordx4 v[90:91], v[82:85], off
	v_max_f32_e32 v81, 0, v81
	v_max_f32_e32 v80, 0, v80
	v_max_f32_e32 v79, 0, v79
	v_max_f32_e32 v78, 0, v78
	v_pk_mul_f32 v[82:83], v[76:77], v[76:77]
	v_pk_mul_f32 v[76:77], v[74:75], v[74:75]
	v_pk_mul_f32 v[80:81], v[80:81], v[80:81]
	v_pk_mul_f32 v[78:79], v[78:79], v[78:79]
	s_nop 0
	v_cvt_pk_bf16_f32 v74, v78, v79
	v_cvt_pk_bf16_f32 v75, v80, v81
	v_cvt_pk_bf16_f32 v76, v76, v77
	v_cvt_pk_bf16_f32 v77, v82, v83
	global_store_dwordx4 v[90:91], v[74:77], off offset:256
	ds_read_b32 v76, v161 offset:512
	s_waitcnt lgkmcnt(0)
	v_pk_mul_f32 v[72:73], v[72:73], v[76:77] op_sel_hi:[1,0]
	v_add_u32_e32 v74, 0x80, v154
	v_ashrrev_i32_e32 v75, 31, v74
	v_lshlrev_b64 v[74:75], 13, v[74:75]
	v_lshl_add_u64 v[74:75], s[30:31], 0, v[74:75]
	v_lshl_add_u64 v[74:75], v[74:75], 0, s[38:39]
	v_pk_mul_f32 v[70:71], v[70:71], v[76:77] op_sel_hi:[1,0]
	v_pk_mul_f32 v[68:69], v[68:69], v[76:77] op_sel_hi:[1,0]
	v_pk_mul_f32 v[66:67], v[66:67], v[76:77] op_sel_hi:[1,0]
	v_lshl_add_u64 v[74:75], v[74:75], 0, s[50:51]
	v_max_f32_e32 v73, 0, v73
	v_max_f32_e32 v72, 0, v72
	v_max_f32_e32 v71, 0, v71
	v_max_f32_e32 v70, 0, v70
	v_max_f32_e32 v69, 0, v69
	v_max_f32_e32 v68, 0, v68
	v_max_f32_e32 v67, 0, v67
	v_max_f32_e32 v66, 0, v66
	v_pk_mul_f32 v[60:61], v[60:61], v[76:77] op_sel_hi:[1,0]
	v_pk_mul_f32 v[58:59], v[58:59], v[76:77] op_sel_hi:[1,0]
	v_lshl_add_u64 v[74:75], v[74:75], 0, v[152:153]
	v_pk_mul_f32 v[72:73], v[72:73], v[72:73]
	v_pk_mul_f32 v[70:71], v[70:71], v[70:71]
	v_pk_mul_f32 v[78:79], v[68:69], v[68:69]
	v_pk_mul_f32 v[68:69], v[66:67], v[66:67]
	v_cvt_pk_bf16_f32 v66, v70, v71
	v_cvt_pk_bf16_f32 v67, v72, v73
	v_pk_mul_f32 v[64:65], v[64:65], v[76:77] op_sel_hi:[1,0]
	v_pk_mul_f32 v[62:63], v[62:63], v[76:77] op_sel_hi:[1,0]
	v_max_f32_e32 v61, 0, v61
	v_max_f32_e32 v60, 0, v60
	v_max_f32_e32 v59, 0, v59
	v_max_f32_e32 v58, 0, v58
	v_cvt_pk_bf16_f32 v68, v68, v69
	v_cvt_pk_bf16_f32 v69, v78, v79
	global_store_dwordx4 v[74:75], v[66:69], off
	v_max_f32_e32 v65, 0, v65
	v_max_f32_e32 v64, 0, v64
	v_max_f32_e32 v63, 0, v63
	v_max_f32_e32 v62, 0, v62
	v_pk_mul_f32 v[66:67], v[60:61], v[60:61]
	v_pk_mul_f32 v[60:61], v[58:59], v[58:59]
	v_pk_mul_f32 v[64:65], v[64:65], v[64:65]
	v_pk_mul_f32 v[62:63], v[62:63], v[62:63]
	s_nop 0
	v_cvt_pk_bf16_f32 v58, v62, v63
	v_cvt_pk_bf16_f32 v59, v64, v65
	v_cvt_pk_bf16_f32 v60, v60, v61
	v_cvt_pk_bf16_f32 v61, v66, v67
	global_store_dwordx4 v[74:75], v[58:61], off offset:256
	ds_read_b32 v60, v161 offset:576
	s_waitcnt lgkmcnt(0)
	v_pk_mul_f32 v[56:57], v[56:57], v[60:61] op_sel_hi:[1,0]
	v_add_u32_e32 v58, 0x90, v154
	v_ashrrev_i32_e32 v59, 31, v58
	v_lshlrev_b64 v[58:59], 13, v[58:59]
	v_lshl_add_u64 v[58:59], s[30:31], 0, v[58:59]
	v_lshl_add_u64 v[58:59], v[58:59], 0, s[38:39]
	v_pk_mul_f32 v[54:55], v[54:55], v[60:61] op_sel_hi:[1,0]
	v_pk_mul_f32 v[52:53], v[52:53], v[60:61] op_sel_hi:[1,0]
	v_pk_mul_f32 v[50:51], v[50:51], v[60:61] op_sel_hi:[1,0]
	v_lshl_add_u64 v[58:59], v[58:59], 0, s[50:51]
	v_max_f32_e32 v57, 0, v57
	v_max_f32_e32 v56, 0, v56
	v_max_f32_e32 v55, 0, v55
	v_max_f32_e32 v54, 0, v54
	v_max_f32_e32 v53, 0, v53
	v_max_f32_e32 v52, 0, v52
	v_max_f32_e32 v51, 0, v51
	v_max_f32_e32 v50, 0, v50
	v_pk_mul_f32 v[44:45], v[44:45], v[60:61] op_sel_hi:[1,0]
	v_pk_mul_f32 v[42:43], v[42:43], v[60:61] op_sel_hi:[1,0]
	v_lshl_add_u64 v[58:59], v[58:59], 0, v[152:153]
	v_pk_mul_f32 v[56:57], v[56:57], v[56:57]
	v_pk_mul_f32 v[54:55], v[54:55], v[54:55]
	v_pk_mul_f32 v[62:63], v[52:53], v[52:53]
	v_pk_mul_f32 v[52:53], v[50:51], v[50:51]
	v_cvt_pk_bf16_f32 v50, v54, v55
	v_cvt_pk_bf16_f32 v51, v56, v57
	v_pk_mul_f32 v[48:49], v[48:49], v[60:61] op_sel_hi:[1,0]
	v_pk_mul_f32 v[46:47], v[46:47], v[60:61] op_sel_hi:[1,0]
	v_max_f32_e32 v45, 0, v45
	v_max_f32_e32 v44, 0, v44
	v_max_f32_e32 v43, 0, v43
	v_max_f32_e32 v42, 0, v42
	v_cvt_pk_bf16_f32 v52, v52, v53
	v_cvt_pk_bf16_f32 v53, v62, v63
	global_store_dwordx4 v[58:59], v[50:53], off
	v_max_f32_e32 v49, 0, v49
	v_max_f32_e32 v48, 0, v48
	v_max_f32_e32 v47, 0, v47
	v_max_f32_e32 v46, 0, v46
	v_pk_mul_f32 v[50:51], v[44:45], v[44:45]
	v_pk_mul_f32 v[44:45], v[42:43], v[42:43]
	v_pk_mul_f32 v[48:49], v[48:49], v[48:49]
	v_pk_mul_f32 v[46:47], v[46:47], v[46:47]
	s_nop 0
	v_cvt_pk_bf16_f32 v42, v46, v47
	v_cvt_pk_bf16_f32 v43, v48, v49
	v_cvt_pk_bf16_f32 v44, v44, v45
	v_cvt_pk_bf16_f32 v45, v50, v51
	global_store_dwordx4 v[58:59], v[42:45], off offset:256
	ds_read_b32 v44, v161 offset:640
	s_waitcnt lgkmcnt(0)
	v_pk_mul_f32 v[40:41], v[40:41], v[44:45] op_sel_hi:[1,0]
	v_add_u32_e32 v42, 0xa0, v154
	v_ashrrev_i32_e32 v43, 31, v42
	v_lshlrev_b64 v[42:43], 13, v[42:43]
	v_lshl_add_u64 v[42:43], s[30:31], 0, v[42:43]
	v_lshl_add_u64 v[42:43], v[42:43], 0, s[38:39]
	v_pk_mul_f32 v[38:39], v[38:39], v[44:45] op_sel_hi:[1,0]
	v_pk_mul_f32 v[36:37], v[36:37], v[44:45] op_sel_hi:[1,0]
	v_pk_mul_f32 v[34:35], v[34:35], v[44:45] op_sel_hi:[1,0]
	v_lshl_add_u64 v[42:43], v[42:43], 0, s[50:51]
	v_max_f32_e32 v41, 0, v41
	v_max_f32_e32 v40, 0, v40
	v_max_f32_e32 v39, 0, v39
	v_max_f32_e32 v38, 0, v38
	v_max_f32_e32 v37, 0, v37
	v_max_f32_e32 v36, 0, v36
	v_max_f32_e32 v35, 0, v35
	v_max_f32_e32 v34, 0, v34
	v_pk_mul_f32 v[28:29], v[28:29], v[44:45] op_sel_hi:[1,0]
	v_pk_mul_f32 v[26:27], v[26:27], v[44:45] op_sel_hi:[1,0]
	v_lshl_add_u64 v[42:43], v[42:43], 0, v[152:153]
	v_pk_mul_f32 v[40:41], v[40:41], v[40:41]
	v_pk_mul_f32 v[38:39], v[38:39], v[38:39]
	v_pk_mul_f32 v[46:47], v[36:37], v[36:37]
	v_pk_mul_f32 v[36:37], v[34:35], v[34:35]
	v_cvt_pk_bf16_f32 v34, v38, v39
	v_cvt_pk_bf16_f32 v35, v40, v41
	v_pk_mul_f32 v[32:33], v[32:33], v[44:45] op_sel_hi:[1,0]
	v_pk_mul_f32 v[30:31], v[30:31], v[44:45] op_sel_hi:[1,0]
	v_max_f32_e32 v29, 0, v29
	v_max_f32_e32 v28, 0, v28
	v_max_f32_e32 v27, 0, v27
	v_max_f32_e32 v26, 0, v26
	v_cvt_pk_bf16_f32 v36, v36, v37
	v_cvt_pk_bf16_f32 v37, v46, v47
	global_store_dwordx4 v[42:43], v[34:37], off
	v_max_f32_e32 v33, 0, v33
	v_max_f32_e32 v32, 0, v32
	v_max_f32_e32 v31, 0, v31
	v_max_f32_e32 v30, 0, v30
	v_pk_mul_f32 v[34:35], v[28:29], v[28:29]
	v_pk_mul_f32 v[28:29], v[26:27], v[26:27]
	v_pk_mul_f32 v[32:33], v[32:33], v[32:33]
	v_pk_mul_f32 v[30:31], v[30:31], v[30:31]
	s_nop 0
	v_cvt_pk_bf16_f32 v26, v30, v31
	v_cvt_pk_bf16_f32 v27, v32, v33
	v_cvt_pk_bf16_f32 v28, v28, v29
	v_cvt_pk_bf16_f32 v29, v34, v35
	global_store_dwordx4 v[42:43], v[26:29], off offset:256
	ds_read_b32 v28, v161 offset:704
	s_waitcnt lgkmcnt(0)
	v_pk_mul_f32 v[24:25], v[24:25], v[28:29] op_sel_hi:[1,0]
	v_add_u32_e32 v26, 0xb0, v154
	v_ashrrev_i32_e32 v27, 31, v26
	v_lshlrev_b64 v[26:27], 13, v[26:27]
	v_lshl_add_u64 v[26:27], s[30:31], 0, v[26:27]
	v_lshl_add_u64 v[26:27], v[26:27], 0, s[38:39]
	v_pk_mul_f32 v[22:23], v[22:23], v[28:29] op_sel_hi:[1,0]
	v_pk_mul_f32 v[20:21], v[20:21], v[28:29] op_sel_hi:[1,0]
	v_pk_mul_f32 v[18:19], v[18:19], v[28:29] op_sel_hi:[1,0]
	v_lshl_add_u64 v[26:27], v[26:27], 0, s[50:51]
	v_max_f32_e32 v25, 0, v25
	v_max_f32_e32 v24, 0, v24
	v_max_f32_e32 v23, 0, v23
	v_max_f32_e32 v22, 0, v22
	v_max_f32_e32 v21, 0, v21
	v_max_f32_e32 v20, 0, v20
	v_max_f32_e32 v19, 0, v19
	v_max_f32_e32 v18, 0, v18
	v_pk_mul_f32 v[12:13], v[12:13], v[28:29] op_sel_hi:[1,0]
	v_pk_mul_f32 v[10:11], v[10:11], v[28:29] op_sel_hi:[1,0]
	v_lshl_add_u64 v[26:27], v[26:27], 0, v[152:153]
	v_pk_mul_f32 v[24:25], v[24:25], v[24:25]
	v_pk_mul_f32 v[22:23], v[22:23], v[22:23]
	v_pk_mul_f32 v[30:31], v[20:21], v[20:21]
	v_pk_mul_f32 v[20:21], v[18:19], v[18:19]
	v_cvt_pk_bf16_f32 v18, v22, v23
	v_cvt_pk_bf16_f32 v19, v24, v25
	v_pk_mul_f32 v[16:17], v[16:17], v[28:29] op_sel_hi:[1,0]
	v_pk_mul_f32 v[14:15], v[14:15], v[28:29] op_sel_hi:[1,0]
	v_max_f32_e32 v13, 0, v13
	v_max_f32_e32 v12, 0, v12
	v_max_f32_e32 v11, 0, v11
	v_max_f32_e32 v10, 0, v10
	v_cvt_pk_bf16_f32 v20, v20, v21
	v_cvt_pk_bf16_f32 v21, v30, v31
	global_store_dwordx4 v[26:27], v[18:21], off
	v_max_f32_e32 v17, 0, v17
	v_max_f32_e32 v16, 0, v16
	v_max_f32_e32 v15, 0, v15
	v_max_f32_e32 v14, 0, v14
	v_pk_mul_f32 v[18:19], v[12:13], v[12:13]
	v_pk_mul_f32 v[12:13], v[10:11], v[10:11]
	v_pk_mul_f32 v[16:17], v[16:17], v[16:17]
	v_pk_mul_f32 v[14:15], v[14:15], v[14:15]
	s_mov_b64 s[38:39], -1
	v_cvt_pk_bf16_f32 v10, v14, v15
	v_cvt_pk_bf16_f32 v11, v16, v17
	v_cvt_pk_bf16_f32 v12, v12, v13
	v_cvt_pk_bf16_f32 v13, v18, v19
	global_store_dwordx4 v[26:27], v[10:13], off offset:256
	s_cbranch_vccnz .LBB0_144
.LBB0_160:
	s_andn2_b64 vcc, exec, s[26:27]
	s_cbranch_vccnz .LBB0_143
	s_barrier
	s_branch .LBB0_143
